# P4 merge epilogue: rolling window of 7 gate/MG load pairs in flight with counted vmcnt (was one load per round trip); stacks on P8 epilogue
# speedup vs baseline: 1.0118x; 1.0118x over previous
; __device__ __forceinline__ unsigned cvt_pk_bf16(float lo, float hi) { unsigned r; asm volatile("v_cvt_pk_bf16_f32 %0, %1, %2" : "=v"(r) : "v"(lo), "v"(hi)); return r; }
; __device__ __forceinline__ float bflo(unsigned w) { return __uint_as_float(w << 16); }
; __device__ __forceinline__ float bfhi(unsigned w) { return __uint_as_float(w & 0xffff0000u); }
;     __device__ __forceinline__ void operator()(const f32x4 (&acc)[2][2][4][2], const Unit& u, int wr, int wc, int fr, int fq) const {
;         const int br = u.pm >= 64 ? 1 : 0, pm = u.pm & 63, pn = u.pn & 7;
;         const int row0 = pm * BM + wr * 64 + fr, col0 = pn * BM + wc * 32 + 8 * fq, gcol = (br ? 4608 : 6656) + col0;
; #pragma unroll
;         for (int ai = 0; ai < 2; ++ai)
; #pragma unroll
;             for (int m = 0; m < 4; ++m) { const size_t row = (size_t)(row0 + ai * HALF + m * 16);
; #pragma unroll
;                 for (int bj = 0; bj < 2; ++bj) {
;                     const u32x4 g = *(const u32x4*)(P + row * PLD + gcol + bj * HALF);
;                     bf16_t* mp = MG + row * 2048 + col0 + bj * HALF;
;                     float v[8];
;                     v[0] = acc[ai][bj][m][0][0] * bflo(g.x); v[1] = acc[ai][bj][m][0][1] * bfhi(g.x); v[2] = acc[ai][bj][m][0][2] * bflo(g.y); v[3] = acc[ai][bj][m][0][3] * bfhi(g.y);
;                     v[4] = acc[ai][bj][m][1][0] * bflo(g.z); v[5] = acc[ai][bj][m][1][1] * bfhi(g.z); v[6] = acc[ai][bj][m][1][2] * bflo(g.w); v[7] = acc[ai][bj][m][1][3] * bfhi(g.w);
;                     if (br) { const u32x4 p = *(const u32x4*)mp;
;                         v[0] += bflo(p.x); v[1] += bfhi(p.x); v[2] += bflo(p.y); v[3] += bfhi(p.y); v[4] += bflo(p.z); v[5] += bfhi(p.z); v[6] += bflo(p.w); v[7] += bfhi(p.w); }
;                     u32x4 w; w.x = cvt_pk_bf16(v[0], v[1]); w.y = cvt_pk_bf16(v[2], v[3]); w.z = cvt_pk_bf16(v[4], v[5]); w.w = cvt_pk_bf16(v[6], v[7]);
;                     *(u32x4*)mp = w; } }
;     }
.LBB0_575:
	s_lshl_b32 s7, s6, 8
	s_lshl_b32 s13, s20, 8
	s_and_b32 s7, s7, 0x3f00
	s_and_b32 s13, s13, 0x700
	v_readlane_b32 s100, v236, 50
	v_readlane_b32 s101, v236, 51
	s_cmp_gt_i32 s6, 63
	s_cselect_b32 s15, s41, 0x1a00
	v_or_b32_e32 v150, s13, v158
	v_add_u32_e32 v148, s7, v156
	v_add_u32_e32 v136, s15, v150
	v_mul_u32_u24_e32 v146, 0x4400, v148
	v_lshl_add_u32 v136, v136, 1, v146
	v_lshlrev_b32_e32 v146, 12, v148
	v_lshl_add_u32 v146, v150, 1, v146
	v_mov_b32_e32 v147, v146
	s_nop 0
	s_cbranch_scc1 .Lp4epi_br1
	global_load_dwordx4 v[164:167], v136, s[72:73]
	global_load_dwordx4 v[172:175], v136, s[72:73] offset:256
	v_add_u32_e32 v136, 0x44000, v136
	global_load_dwordx4 v[192:195], v136, s[72:73]
	global_load_dwordx4 v[200:203], v136, s[72:73] offset:256
	v_add_u32_e32 v136, 0x44000, v136
	global_load_dwordx4 v[208:211], v136, s[72:73]
	global_load_dwordx4 v[216:219], v136, s[72:73] offset:256
	v_add_u32_e32 v136, 0x44000, v136
	global_load_dwordx4 v[180:183], v136, s[72:73]
	s_waitcnt vmcnt(6)
	v_lshlrev_b32_e32 v148, 16, v164
	v_and_b32_e32 v149, 0xffff0000, v164
	v_lshlrev_b32_e32 v150, 16, v165
	v_and_b32_e32 v151, 0xffff0000, v165
	v_lshlrev_b32_e32 v152, 16, v166
	v_and_b32_e32 v153, 0xffff0000, v166
	v_lshlrev_b32_e32 v154, 16, v167
	v_and_b32_e32 v155, 0xffff0000, v167
	v_pk_mul_f32 v[124:125], v[124:125], v[148:149]
	v_pk_mul_f32 v[126:127], v[126:127], v[150:151]
	v_pk_mul_f32 v[120:121], v[120:121], v[152:153]
	v_pk_mul_f32 v[122:123], v[122:123], v[154:155]
	v_cvt_pk_bf16_f32 v164, v124, v125
	v_cvt_pk_bf16_f32 v165, v126, v127
	v_cvt_pk_bf16_f32 v166, v120, v121
	v_cvt_pk_bf16_f32 v167, v122, v123
	global_store_dwordx4 v147, v[164:167], s[100:101]
	s_nop 1
	global_load_dwordx4 v[164:167], v136, s[72:73] offset:256
	v_add_u32_e32 v136, 0x154000, v136
	s_waitcnt vmcnt(7)
	v_lshlrev_b32_e32 v148, 16, v172
	v_and_b32_e32 v149, 0xffff0000, v172
	v_lshlrev_b32_e32 v150, 16, v173
	v_and_b32_e32 v151, 0xffff0000, v173
	v_lshlrev_b32_e32 v152, 16, v174
	v_and_b32_e32 v153, 0xffff0000, v174
	v_lshlrev_b32_e32 v154, 16, v175
	v_and_b32_e32 v155, 0xffff0000, v175
	v_pk_mul_f32 v[116:117], v[116:117], v[148:149]
	v_pk_mul_f32 v[118:119], v[118:119], v[150:151]
	v_pk_mul_f32 v[112:113], v[112:113], v[152:153]
	v_pk_mul_f32 v[114:115], v[114:115], v[154:155]
	v_cvt_pk_bf16_f32 v172, v116, v117
	v_cvt_pk_bf16_f32 v173, v118, v119
	v_cvt_pk_bf16_f32 v174, v112, v113
	v_cvt_pk_bf16_f32 v175, v114, v115
	global_store_dwordx4 v147, v[172:175], s[100:101] offset:256
	v_add_u32_e32 v147, 0x10000, v147
	s_nop 1
	global_load_dwordx4 v[172:175], v136, s[72:73]
	s_waitcnt vmcnt(8)
	v_lshlrev_b32_e32 v148, 16, v192
	v_and_b32_e32 v149, 0xffff0000, v192
	v_lshlrev_b32_e32 v150, 16, v193
	v_and_b32_e32 v151, 0xffff0000, v193
	v_lshlrev_b32_e32 v152, 16, v194
	v_and_b32_e32 v153, 0xffff0000, v194
	v_lshlrev_b32_e32 v154, 16, v195
	v_and_b32_e32 v155, 0xffff0000, v195
	v_pk_mul_f32 v[108:109], v[108:109], v[148:149]
	v_pk_mul_f32 v[110:111], v[110:111], v[150:151]
	v_pk_mul_f32 v[104:105], v[104:105], v[152:153]
	v_pk_mul_f32 v[106:107], v[106:107], v[154:155]
	v_cvt_pk_bf16_f32 v192, v108, v109
	v_cvt_pk_bf16_f32 v193, v110, v111
	v_cvt_pk_bf16_f32 v194, v104, v105
	v_cvt_pk_bf16_f32 v195, v106, v107
	global_store_dwordx4 v147, v[192:195], s[100:101]
	s_nop 1
	global_load_dwordx4 v[192:195], v136, s[72:73] offset:256
	v_add_u32_e32 v136, 0x44000, v136
	s_waitcnt vmcnt(9)
	v_lshlrev_b32_e32 v148, 16, v200
	v_and_b32_e32 v149, 0xffff0000, v200
	v_lshlrev_b32_e32 v150, 16, v201
	v_and_b32_e32 v151, 0xffff0000, v201
	v_lshlrev_b32_e32 v152, 16, v202
	v_and_b32_e32 v153, 0xffff0000, v202
	v_lshlrev_b32_e32 v154, 16, v203
	v_and_b32_e32 v155, 0xffff0000, v203
	v_pk_mul_f32 v[100:101], v[100:101], v[148:149]
	v_pk_mul_f32 v[102:103], v[102:103], v[150:151]
	v_pk_mul_f32 v[96:97], v[96:97], v[152:153]
	v_pk_mul_f32 v[98:99], v[98:99], v[154:155]
	v_cvt_pk_bf16_f32 v200, v100, v101
	v_cvt_pk_bf16_f32 v201, v102, v103
	v_cvt_pk_bf16_f32 v202, v96, v97
	v_cvt_pk_bf16_f32 v203, v98, v99
	global_store_dwordx4 v147, v[200:203], s[100:101] offset:256
	v_add_u32_e32 v147, 0x10000, v147
	s_nop 1
	global_load_dwordx4 v[200:203], v136, s[72:73]
	s_waitcnt vmcnt(10)
	v_lshlrev_b32_e32 v148, 16, v208
	v_and_b32_e32 v149, 0xffff0000, v208
	v_lshlrev_b32_e32 v150, 16, v209
	v_and_b32_e32 v151, 0xffff0000, v209
	v_lshlrev_b32_e32 v152, 16, v210
	v_and_b32_e32 v153, 0xffff0000, v210
	v_lshlrev_b32_e32 v154, 16, v211
	v_and_b32_e32 v155, 0xffff0000, v211
	v_pk_mul_f32 v[92:93], v[92:93], v[148:149]
	v_pk_mul_f32 v[94:95], v[94:95], v[150:151]
	v_pk_mul_f32 v[88:89], v[88:89], v[152:153]
	v_pk_mul_f32 v[90:91], v[90:91], v[154:155]
	v_cvt_pk_bf16_f32 v208, v92, v93
	v_cvt_pk_bf16_f32 v209, v94, v95
	v_cvt_pk_bf16_f32 v210, v88, v89
	v_cvt_pk_bf16_f32 v211, v90, v91
	global_store_dwordx4 v147, v[208:211], s[100:101]
	s_nop 1
	global_load_dwordx4 v[208:211], v136, s[72:73] offset:256
	v_add_u32_e32 v136, 0x44000, v136
	s_waitcnt vmcnt(11)
	v_lshlrev_b32_e32 v148, 16, v216
	v_and_b32_e32 v149, 0xffff0000, v216
	v_lshlrev_b32_e32 v150, 16, v217
	v_and_b32_e32 v151, 0xffff0000, v217
	v_lshlrev_b32_e32 v152, 16, v218
	v_and_b32_e32 v153, 0xffff0000, v218
	v_lshlrev_b32_e32 v154, 16, v219
	v_and_b32_e32 v155, 0xffff0000, v219
	v_pk_mul_f32 v[84:85], v[84:85], v[148:149]
	v_pk_mul_f32 v[86:87], v[86:87], v[150:151]
	v_pk_mul_f32 v[80:81], v[80:81], v[152:153]
	v_pk_mul_f32 v[82:83], v[82:83], v[154:155]
	v_cvt_pk_bf16_f32 v216, v84, v85
	v_cvt_pk_bf16_f32 v217, v86, v87
	v_cvt_pk_bf16_f32 v218, v80, v81
	v_cvt_pk_bf16_f32 v219, v82, v83
	global_store_dwordx4 v147, v[216:219], s[100:101] offset:256
	v_add_u32_e32 v147, 0x10000, v147
	s_nop 1
	global_load_dwordx4 v[216:219], v136, s[72:73]
	s_waitcnt vmcnt(12)
; __device__ __forceinline__ unsigned cvt_pk_bf16(float lo, float hi) { unsigned r; asm volatile("v_cvt_pk_bf16_f32 %0, %1, %2" : "=v"(r) : "v"(lo), "v"(hi)); return r; }
; __device__ __forceinline__ float bflo(unsigned w) { return __uint_as_float(w << 16); }
; __device__ __forceinline__ float bfhi(unsigned w) { return __uint_as_float(w & 0xffff0000u); }
;     __device__ __forceinline__ void operator()(const f32x4 (&acc)[2][2][4][2], const Unit& u, int wr, int wc, int fr, int fq) const {
;     ...
;         for (int ai = 0; ai < 2; ++ai)
; #pragma unroll
;             for (int m = 0; m < 4; ++m) { const size_t row = (size_t)(row0 + ai * HALF + m * 16);
; #pragma unroll
;                 for (int bj = 0; bj < 2; ++bj) {
;                     const u32x4 g = *(const u32x4*)(P + row * PLD + gcol + bj * HALF);
;                     bf16_t* mp = MG + row * 2048 + col0 + bj * HALF;
;                     float v[8];
;                     v[0] = acc[ai][bj][m][0][0] * bflo(g.x); v[1] = acc[ai][bj][m][0][1] * bfhi(g.x); v[2] = acc[ai][bj][m][0][2] * bflo(g.y); v[3] = acc[ai][bj][m][0][3] * bfhi(g.y);
;                     v[4] = acc[ai][bj][m][1][0] * bflo(g.z); v[5] = acc[ai][bj][m][1][1] * bfhi(g.z); v[6] = acc[ai][bj][m][1][2] * bflo(g.w); v[7] = acc[ai][bj][m][1][3] * bfhi(g.w);
;                     if (br) { const u32x4 p = *(const u32x4*)mp;
;                         v[0] += bflo(p.x); v[1] += bfhi(p.x); v[2] += bflo(p.y); v[3] += bfhi(p.y); v[4] += bflo(p.z); v[5] += bfhi(p.z); v[6] += bflo(p.w); v[7] += bfhi(p.w); }
;                     u32x4 w; w.x = cvt_pk_bf16(v[0], v[1]); w.y = cvt_pk_bf16(v[2], v[3]); w.z = cvt_pk_bf16(v[4], v[5]); w.w = cvt_pk_bf16(v[6], v[7]);
;                     *(u32x4*)mp = w; } }
	v_lshlrev_b32_e32 v148, 16, v180
	v_and_b32_e32 v149, 0xffff0000, v180
	v_lshlrev_b32_e32 v150, 16, v181
	v_and_b32_e32 v151, 0xffff0000, v181
	v_lshlrev_b32_e32 v152, 16, v182
	v_and_b32_e32 v153, 0xffff0000, v182
	v_lshlrev_b32_e32 v154, 16, v183
	v_and_b32_e32 v155, 0xffff0000, v183
	v_pk_mul_f32 v[76:77], v[76:77], v[148:149]
	v_pk_mul_f32 v[78:79], v[78:79], v[150:151]
	v_pk_mul_f32 v[72:73], v[72:73], v[152:153]
	v_pk_mul_f32 v[74:75], v[74:75], v[154:155]
	v_cvt_pk_bf16_f32 v180, v76, v77
	v_cvt_pk_bf16_f32 v181, v78, v79
	v_cvt_pk_bf16_f32 v182, v72, v73
	v_cvt_pk_bf16_f32 v183, v74, v75
	global_store_dwordx4 v147, v[180:183], s[100:101]
	s_nop 1
	global_load_dwordx4 v[180:183], v136, s[72:73] offset:256
	v_add_u32_e32 v136, 0x44000, v136
	s_waitcnt vmcnt(12)
	v_lshlrev_b32_e32 v148, 16, v164
	v_and_b32_e32 v149, 0xffff0000, v164
	v_lshlrev_b32_e32 v150, 16, v165
	v_and_b32_e32 v151, 0xffff0000, v165
	v_lshlrev_b32_e32 v152, 16, v166
	v_and_b32_e32 v153, 0xffff0000, v166
	v_lshlrev_b32_e32 v154, 16, v167
	v_and_b32_e32 v155, 0xffff0000, v167
	v_pk_mul_f32 v[68:69], v[68:69], v[148:149]
	v_pk_mul_f32 v[70:71], v[70:71], v[150:151]
	v_pk_mul_f32 v[64:65], v[64:65], v[152:153]
	v_pk_mul_f32 v[66:67], v[66:67], v[154:155]
	v_cvt_pk_bf16_f32 v164, v68, v69
	v_cvt_pk_bf16_f32 v165, v70, v71
	v_cvt_pk_bf16_f32 v166, v64, v65
	v_cvt_pk_bf16_f32 v167, v66, v67
	global_store_dwordx4 v147, v[164:167], s[100:101] offset:256
	v_add_u32_e32 v147, 0x50000, v147
	s_nop 1
	global_load_dwordx4 v[164:167], v136, s[72:73]
	s_waitcnt vmcnt(12)
	v_lshlrev_b32_e32 v148, 16, v172
	v_and_b32_e32 v149, 0xffff0000, v172
	v_lshlrev_b32_e32 v150, 16, v173
	v_and_b32_e32 v151, 0xffff0000, v173
	v_lshlrev_b32_e32 v152, 16, v174
	v_and_b32_e32 v153, 0xffff0000, v174
	v_lshlrev_b32_e32 v154, 16, v175
	v_and_b32_e32 v155, 0xffff0000, v175
	v_pk_mul_f32 v[60:61], v[60:61], v[148:149]
	v_pk_mul_f32 v[62:63], v[62:63], v[150:151]
	v_pk_mul_f32 v[56:57], v[56:57], v[152:153]
	v_pk_mul_f32 v[58:59], v[58:59], v[154:155]
	v_cvt_pk_bf16_f32 v172, v60, v61
	v_cvt_pk_bf16_f32 v173, v62, v63
	v_cvt_pk_bf16_f32 v174, v56, v57
	v_cvt_pk_bf16_f32 v175, v58, v59
	global_store_dwordx4 v147, v[172:175], s[100:101]
	s_nop 1
	global_load_dwordx4 v[172:175], v136, s[72:73] offset:256
	s_waitcnt vmcnt(12)
	v_lshlrev_b32_e32 v148, 16, v192
	v_and_b32_e32 v149, 0xffff0000, v192
	v_lshlrev_b32_e32 v150, 16, v193
	v_and_b32_e32 v151, 0xffff0000, v193
	v_lshlrev_b32_e32 v152, 16, v194
	v_and_b32_e32 v153, 0xffff0000, v194
	v_lshlrev_b32_e32 v154, 16, v195
	v_and_b32_e32 v155, 0xffff0000, v195
	v_pk_mul_f32 v[52:53], v[52:53], v[148:149]
	v_pk_mul_f32 v[54:55], v[54:55], v[150:151]
	v_pk_mul_f32 v[48:49], v[48:49], v[152:153]
	v_pk_mul_f32 v[50:51], v[50:51], v[154:155]
	v_cvt_pk_bf16_f32 v192, v52, v53
	v_cvt_pk_bf16_f32 v193, v54, v55
	v_cvt_pk_bf16_f32 v194, v48, v49
	v_cvt_pk_bf16_f32 v195, v50, v51
	global_store_dwordx4 v147, v[192:195], s[100:101] offset:256
	v_add_u32_e32 v147, 0x10000, v147
	s_waitcnt vmcnt(11)
	v_lshlrev_b32_e32 v148, 16, v200
	v_and_b32_e32 v149, 0xffff0000, v200
	v_lshlrev_b32_e32 v150, 16, v201
	v_and_b32_e32 v151, 0xffff0000, v201
	v_lshlrev_b32_e32 v152, 16, v202
	v_and_b32_e32 v153, 0xffff0000, v202
	v_lshlrev_b32_e32 v154, 16, v203
	v_and_b32_e32 v155, 0xffff0000, v203
	v_pk_mul_f32 v[44:45], v[44:45], v[148:149]
	v_pk_mul_f32 v[46:47], v[46:47], v[150:151]
	v_pk_mul_f32 v[40:41], v[40:41], v[152:153]
	v_pk_mul_f32 v[42:43], v[42:43], v[154:155]
	v_cvt_pk_bf16_f32 v200, v44, v45
	v_cvt_pk_bf16_f32 v201, v46, v47
	v_cvt_pk_bf16_f32 v202, v40, v41
	v_cvt_pk_bf16_f32 v203, v42, v43
	global_store_dwordx4 v147, v[200:203], s[100:101]
	s_waitcnt vmcnt(10)
	v_lshlrev_b32_e32 v148, 16, v208
	v_and_b32_e32 v149, 0xffff0000, v208
	v_lshlrev_b32_e32 v150, 16, v209
	v_and_b32_e32 v151, 0xffff0000, v209
	v_lshlrev_b32_e32 v152, 16, v210
	v_and_b32_e32 v153, 0xffff0000, v210
	v_lshlrev_b32_e32 v154, 16, v211
	v_and_b32_e32 v155, 0xffff0000, v211
	v_pk_mul_f32 v[36:37], v[36:37], v[148:149]
	v_pk_mul_f32 v[38:39], v[38:39], v[150:151]
	v_pk_mul_f32 v[32:33], v[32:33], v[152:153]
	v_pk_mul_f32 v[34:35], v[34:35], v[154:155]
	v_cvt_pk_bf16_f32 v208, v36, v37
	v_cvt_pk_bf16_f32 v209, v38, v39
	v_cvt_pk_bf16_f32 v210, v32, v33
	v_cvt_pk_bf16_f32 v211, v34, v35
	global_store_dwordx4 v147, v[208:211], s[100:101] offset:256
	v_add_u32_e32 v147, 0x10000, v147
	s_waitcnt vmcnt(9)
	v_lshlrev_b32_e32 v148, 16, v216
	v_and_b32_e32 v149, 0xffff0000, v216
	v_lshlrev_b32_e32 v150, 16, v217
	v_and_b32_e32 v151, 0xffff0000, v217
	v_lshlrev_b32_e32 v152, 16, v218
	v_and_b32_e32 v153, 0xffff0000, v218
	v_lshlrev_b32_e32 v154, 16, v219
	v_and_b32_e32 v155, 0xffff0000, v219
	v_pk_mul_f32 v[28:29], v[28:29], v[148:149]
	v_pk_mul_f32 v[30:31], v[30:31], v[150:151]
	v_pk_mul_f32 v[24:25], v[24:25], v[152:153]
	v_pk_mul_f32 v[26:27], v[26:27], v[154:155]
	v_cvt_pk_bf16_f32 v216, v28, v29
	v_cvt_pk_bf16_f32 v217, v30, v31
	v_cvt_pk_bf16_f32 v218, v24, v25
	v_cvt_pk_bf16_f32 v219, v26, v27
	global_store_dwordx4 v147, v[216:219], s[100:101]
	s_waitcnt vmcnt(8)
	v_lshlrev_b32_e32 v148, 16, v180
	v_and_b32_e32 v149, 0xffff0000, v180
	v_lshlrev_b32_e32 v150, 16, v181
	v_and_b32_e32 v151, 0xffff0000, v181
	v_lshlrev_b32_e32 v152, 16, v182
	v_and_b32_e32 v153, 0xffff0000, v182
	v_lshlrev_b32_e32 v154, 16, v183
	v_and_b32_e32 v155, 0xffff0000, v183
	v_pk_mul_f32 v[20:21], v[20:21], v[148:149]
	v_pk_mul_f32 v[22:23], v[22:23], v[150:151]
	v_pk_mul_f32 v[16:17], v[16:17], v[152:153]
	v_pk_mul_f32 v[18:19], v[18:19], v[154:155]
	v_cvt_pk_bf16_f32 v180, v20, v21
	v_cvt_pk_bf16_f32 v181, v22, v23
	v_cvt_pk_bf16_f32 v182, v16, v17
	v_cvt_pk_bf16_f32 v183, v18, v19
	global_store_dwordx4 v147, v[180:183], s[100:101] offset:256
	v_add_u32_e32 v147, 0x10000, v147
	s_waitcnt vmcnt(7)
; __device__ __forceinline__ unsigned cvt_pk_bf16(float lo, float hi) { unsigned r; asm volatile("v_cvt_pk_bf16_f32 %0, %1, %2" : "=v"(r) : "v"(lo), "v"(hi)); return r; }
; __device__ __forceinline__ float bflo(unsigned w) { return __uint_as_float(w << 16); }
; __device__ __forceinline__ float bfhi(unsigned w) { return __uint_as_float(w & 0xffff0000u); }
;     __device__ __forceinline__ void operator()(const f32x4 (&acc)[2][2][4][2], const Unit& u, int wr, int wc, int fr, int fq) const {
;     ...
;                     const u32x4 g = *(const u32x4*)(P + row * PLD + gcol + bj * HALF);
;                     bf16_t* mp = MG + row * 2048 + col0 + bj * HALF;
;                     float v[8];
;                     v[0] = acc[ai][bj][m][0][0] * bflo(g.x); v[1] = acc[ai][bj][m][0][1] * bfhi(g.x); v[2] = acc[ai][bj][m][0][2] * bflo(g.y); v[3] = acc[ai][bj][m][0][3] * bfhi(g.y);
;                     v[4] = acc[ai][bj][m][1][0] * bflo(g.z); v[5] = acc[ai][bj][m][1][1] * bfhi(g.z); v[6] = acc[ai][bj][m][1][2] * bflo(g.w); v[7] = acc[ai][bj][m][1][3] * bfhi(g.w);
;                     if (br) { const u32x4 p = *(const u32x4*)mp;
;                         v[0] += bflo(p.x); v[1] += bfhi(p.x); v[2] += bflo(p.y); v[3] += bfhi(p.y); v[4] += bflo(p.z); v[5] += bfhi(p.z); v[6] += bflo(p.w); v[7] += bfhi(p.w); }
;                     u32x4 w; w.x = cvt_pk_bf16(v[0], v[1]); w.y = cvt_pk_bf16(v[2], v[3]); w.z = cvt_pk_bf16(v[4], v[5]); w.w = cvt_pk_bf16(v[6], v[7]);
;                     *(u32x4*)mp = w; } }
	v_lshlrev_b32_e32 v148, 16, v164
	v_and_b32_e32 v149, 0xffff0000, v164
	v_lshlrev_b32_e32 v150, 16, v165
	v_and_b32_e32 v151, 0xffff0000, v165
	v_lshlrev_b32_e32 v152, 16, v166
	v_and_b32_e32 v153, 0xffff0000, v166
	v_lshlrev_b32_e32 v154, 16, v167
	v_and_b32_e32 v155, 0xffff0000, v167
	v_pk_mul_f32 v[12:13], v[12:13], v[148:149]
	v_pk_mul_f32 v[14:15], v[14:15], v[150:151]
	v_pk_mul_f32 v[8:9], v[8:9], v[152:153]
	v_pk_mul_f32 v[10:11], v[10:11], v[154:155]
	v_cvt_pk_bf16_f32 v164, v12, v13
	v_cvt_pk_bf16_f32 v165, v14, v15
	v_cvt_pk_bf16_f32 v166, v8, v9
	v_cvt_pk_bf16_f32 v167, v10, v11
	global_store_dwordx4 v147, v[164:167], s[100:101]
	s_waitcnt vmcnt(6)
	v_lshlrev_b32_e32 v148, 16, v172
	v_and_b32_e32 v149, 0xffff0000, v172
	v_lshlrev_b32_e32 v150, 16, v173
	v_and_b32_e32 v151, 0xffff0000, v173
	v_lshlrev_b32_e32 v152, 16, v174
	v_and_b32_e32 v153, 0xffff0000, v174
	v_lshlrev_b32_e32 v154, 16, v175
	v_and_b32_e32 v155, 0xffff0000, v175
	v_pk_mul_f32 v[4:5], v[4:5], v[148:149]
	v_pk_mul_f32 v[6:7], v[6:7], v[150:151]
	v_pk_mul_f32 v[0:1], v[0:1], v[152:153]
	v_pk_mul_f32 v[2:3], v[2:3], v[154:155]
	v_cvt_pk_bf16_f32 v172, v4, v5
	v_cvt_pk_bf16_f32 v173, v6, v7
	v_cvt_pk_bf16_f32 v174, v0, v1
	v_cvt_pk_bf16_f32 v175, v2, v3
	global_store_dwordx4 v147, v[172:175], s[100:101] offset:256
	s_branch .Lp4epi_done
.Lp4epi_br1:
	global_load_dwordx4 v[164:167], v136, s[72:73]
	global_load_dwordx4 v[168:171], v146, s[100:101]
	global_load_dwordx4 v[172:175], v136, s[72:73] offset:256
	global_load_dwordx4 v[176:179], v146, s[100:101] offset:256
	v_add_u32_e32 v136, 0x44000, v136
	v_add_u32_e32 v146, 0x10000, v146
	global_load_dwordx4 v[192:195], v136, s[72:73]
	global_load_dwordx4 v[196:199], v146, s[100:101]
	global_load_dwordx4 v[200:203], v136, s[72:73] offset:256
	global_load_dwordx4 v[204:207], v146, s[100:101] offset:256
	v_add_u32_e32 v136, 0x44000, v136
	v_add_u32_e32 v146, 0x10000, v146
	global_load_dwordx4 v[208:211], v136, s[72:73]
	global_load_dwordx4 v[212:215], v146, s[100:101]
	global_load_dwordx4 v[216:219], v136, s[72:73] offset:256
	global_load_dwordx4 v[220:223], v146, s[100:101] offset:256
	v_add_u32_e32 v136, 0x44000, v136
	v_add_u32_e32 v146, 0x10000, v146
	global_load_dwordx4 v[180:183], v136, s[72:73]
	global_load_dwordx4 v[188:191], v146, s[100:101]
	s_waitcnt vmcnt(12)
	v_lshlrev_b32_e32 v148, 16, v164
	v_and_b32_e32 v149, 0xffff0000, v164
	v_lshlrev_b32_e32 v150, 16, v165
	v_and_b32_e32 v151, 0xffff0000, v165
	v_lshlrev_b32_e32 v152, 16, v166
	v_and_b32_e32 v153, 0xffff0000, v166
	v_lshlrev_b32_e32 v154, 16, v167
	v_and_b32_e32 v155, 0xffff0000, v167
	v_pk_mul_f32 v[124:125], v[124:125], v[148:149]
	v_pk_mul_f32 v[126:127], v[126:127], v[150:151]
	v_pk_mul_f32 v[120:121], v[120:121], v[152:153]
	v_pk_mul_f32 v[122:123], v[122:123], v[154:155]
	v_lshlrev_b32_e32 v148, 16, v168
	v_and_b32_e32 v149, 0xffff0000, v168
	v_lshlrev_b32_e32 v150, 16, v169
	v_and_b32_e32 v151, 0xffff0000, v169
	v_lshlrev_b32_e32 v152, 16, v170
	v_and_b32_e32 v153, 0xffff0000, v170
	v_lshlrev_b32_e32 v154, 16, v171
	v_and_b32_e32 v155, 0xffff0000, v171
	v_pk_add_f32 v[124:125], v[124:125], v[148:149]
	v_pk_add_f32 v[126:127], v[126:127], v[150:151]
	v_pk_add_f32 v[120:121], v[120:121], v[152:153]
	v_pk_add_f32 v[122:123], v[122:123], v[154:155]
	v_cvt_pk_bf16_f32 v164, v124, v125
	v_cvt_pk_bf16_f32 v165, v126, v127
	v_cvt_pk_bf16_f32 v166, v120, v121
	v_cvt_pk_bf16_f32 v167, v122, v123
	global_store_dwordx4 v147, v[164:167], s[100:101]
	s_nop 1
	global_load_dwordx4 v[164:167], v136, s[72:73] offset:256
	global_load_dwordx4 v[168:171], v146, s[100:101] offset:256
	v_add_u32_e32 v136, 0x154000, v136
	v_add_u32_e32 v146, 0x50000, v146
	s_waitcnt vmcnt(13)
	v_lshlrev_b32_e32 v148, 16, v172
	v_and_b32_e32 v149, 0xffff0000, v172
	v_lshlrev_b32_e32 v150, 16, v173
	v_and_b32_e32 v151, 0xffff0000, v173
	v_lshlrev_b32_e32 v152, 16, v174
	v_and_b32_e32 v153, 0xffff0000, v174
	v_lshlrev_b32_e32 v154, 16, v175
	v_and_b32_e32 v155, 0xffff0000, v175
	v_pk_mul_f32 v[116:117], v[116:117], v[148:149]
	v_pk_mul_f32 v[118:119], v[118:119], v[150:151]
	v_pk_mul_f32 v[112:113], v[112:113], v[152:153]
	v_pk_mul_f32 v[114:115], v[114:115], v[154:155]
	v_lshlrev_b32_e32 v148, 16, v176
	v_and_b32_e32 v149, 0xffff0000, v176
	v_lshlrev_b32_e32 v150, 16, v177
	v_and_b32_e32 v151, 0xffff0000, v177
	v_lshlrev_b32_e32 v152, 16, v178
	v_and_b32_e32 v153, 0xffff0000, v178
	v_lshlrev_b32_e32 v154, 16, v179
	v_and_b32_e32 v155, 0xffff0000, v179
	v_pk_add_f32 v[116:117], v[116:117], v[148:149]
	v_pk_add_f32 v[118:119], v[118:119], v[150:151]
	v_pk_add_f32 v[112:113], v[112:113], v[152:153]
	v_pk_add_f32 v[114:115], v[114:115], v[154:155]
	v_cvt_pk_bf16_f32 v172, v116, v117
	v_cvt_pk_bf16_f32 v173, v118, v119
	v_cvt_pk_bf16_f32 v174, v112, v113
	v_cvt_pk_bf16_f32 v175, v114, v115
	global_store_dwordx4 v147, v[172:175], s[100:101] offset:256
	v_add_u32_e32 v147, 0x10000, v147
	s_nop 1
	global_load_dwordx4 v[172:175], v136, s[72:73]
	global_load_dwordx4 v[176:179], v146, s[100:101]
	s_waitcnt vmcnt(14)
; __device__ __forceinline__ unsigned cvt_pk_bf16(float lo, float hi) { unsigned r; asm volatile("v_cvt_pk_bf16_f32 %0, %1, %2" : "=v"(r) : "v"(lo), "v"(hi)); return r; }
; __device__ __forceinline__ float bflo(unsigned w) { return __uint_as_float(w << 16); }
; __device__ __forceinline__ float bfhi(unsigned w) { return __uint_as_float(w & 0xffff0000u); }
;     __device__ __forceinline__ void operator()(const f32x4 (&acc)[2][2][4][2], const Unit& u, int wr, int wc, int fr, int fq) const {
;     ...
;                     const u32x4 g = *(const u32x4*)(P + row * PLD + gcol + bj * HALF);
;                     bf16_t* mp = MG + row * 2048 + col0 + bj * HALF;
;                     float v[8];
;                     v[0] = acc[ai][bj][m][0][0] * bflo(g.x); v[1] = acc[ai][bj][m][0][1] * bfhi(g.x); v[2] = acc[ai][bj][m][0][2] * bflo(g.y); v[3] = acc[ai][bj][m][0][3] * bfhi(g.y);
;                     v[4] = acc[ai][bj][m][1][0] * bflo(g.z); v[5] = acc[ai][bj][m][1][1] * bfhi(g.z); v[6] = acc[ai][bj][m][1][2] * bflo(g.w); v[7] = acc[ai][bj][m][1][3] * bfhi(g.w);
;                     if (br) { const u32x4 p = *(const u32x4*)mp;
;                         v[0] += bflo(p.x); v[1] += bfhi(p.x); v[2] += bflo(p.y); v[3] += bfhi(p.y); v[4] += bflo(p.z); v[5] += bfhi(p.z); v[6] += bflo(p.w); v[7] += bfhi(p.w); }
;                     u32x4 w; w.x = cvt_pk_bf16(v[0], v[1]); w.y = cvt_pk_bf16(v[2], v[3]); w.z = cvt_pk_bf16(v[4], v[5]); w.w = cvt_pk_bf16(v[6], v[7]);
;                     *(u32x4*)mp = w; } }
	v_lshlrev_b32_e32 v148, 16, v192
	v_and_b32_e32 v149, 0xffff0000, v192
	v_lshlrev_b32_e32 v150, 16, v193
	v_and_b32_e32 v151, 0xffff0000, v193
	v_lshlrev_b32_e32 v152, 16, v194
	v_and_b32_e32 v153, 0xffff0000, v194
	v_lshlrev_b32_e32 v154, 16, v195
	v_and_b32_e32 v155, 0xffff0000, v195
	v_pk_mul_f32 v[108:109], v[108:109], v[148:149]
	v_pk_mul_f32 v[110:111], v[110:111], v[150:151]
	v_pk_mul_f32 v[104:105], v[104:105], v[152:153]
	v_pk_mul_f32 v[106:107], v[106:107], v[154:155]
	v_lshlrev_b32_e32 v148, 16, v196
	v_and_b32_e32 v149, 0xffff0000, v196
	v_lshlrev_b32_e32 v150, 16, v197
	v_and_b32_e32 v151, 0xffff0000, v197
	v_lshlrev_b32_e32 v152, 16, v198
	v_and_b32_e32 v153, 0xffff0000, v198
	v_lshlrev_b32_e32 v154, 16, v199
	v_and_b32_e32 v155, 0xffff0000, v199
	v_pk_add_f32 v[108:109], v[108:109], v[148:149]
	v_pk_add_f32 v[110:111], v[110:111], v[150:151]
	v_pk_add_f32 v[104:105], v[104:105], v[152:153]
	v_pk_add_f32 v[106:107], v[106:107], v[154:155]
	v_cvt_pk_bf16_f32 v192, v108, v109
	v_cvt_pk_bf16_f32 v193, v110, v111
	v_cvt_pk_bf16_f32 v194, v104, v105
	v_cvt_pk_bf16_f32 v195, v106, v107
	global_store_dwordx4 v147, v[192:195], s[100:101]
	s_nop 1
	global_load_dwordx4 v[192:195], v136, s[72:73] offset:256
	global_load_dwordx4 v[196:199], v146, s[100:101] offset:256
	v_add_u32_e32 v136, 0x44000, v136
	v_add_u32_e32 v146, 0x10000, v146
	s_waitcnt vmcnt(15)
	v_lshlrev_b32_e32 v148, 16, v200
	v_and_b32_e32 v149, 0xffff0000, v200
	v_lshlrev_b32_e32 v150, 16, v201
	v_and_b32_e32 v151, 0xffff0000, v201
	v_lshlrev_b32_e32 v152, 16, v202
	v_and_b32_e32 v153, 0xffff0000, v202
	v_lshlrev_b32_e32 v154, 16, v203
	v_and_b32_e32 v155, 0xffff0000, v203
	v_pk_mul_f32 v[100:101], v[100:101], v[148:149]
	v_pk_mul_f32 v[102:103], v[102:103], v[150:151]
	v_pk_mul_f32 v[96:97], v[96:97], v[152:153]
	v_pk_mul_f32 v[98:99], v[98:99], v[154:155]
	v_lshlrev_b32_e32 v148, 16, v204
	v_and_b32_e32 v149, 0xffff0000, v204
	v_lshlrev_b32_e32 v150, 16, v205
	v_and_b32_e32 v151, 0xffff0000, v205
	v_lshlrev_b32_e32 v152, 16, v206
	v_and_b32_e32 v153, 0xffff0000, v206
	v_lshlrev_b32_e32 v154, 16, v207
	v_and_b32_e32 v155, 0xffff0000, v207
	v_pk_add_f32 v[100:101], v[100:101], v[148:149]
	v_pk_add_f32 v[102:103], v[102:103], v[150:151]
	v_pk_add_f32 v[96:97], v[96:97], v[152:153]
	v_pk_add_f32 v[98:99], v[98:99], v[154:155]
	v_cvt_pk_bf16_f32 v200, v100, v101
	v_cvt_pk_bf16_f32 v201, v102, v103
	v_cvt_pk_bf16_f32 v202, v96, v97
	v_cvt_pk_bf16_f32 v203, v98, v99
	global_store_dwordx4 v147, v[200:203], s[100:101] offset:256
	v_add_u32_e32 v147, 0x10000, v147
	s_nop 1
	global_load_dwordx4 v[200:203], v136, s[72:73]
	global_load_dwordx4 v[204:207], v146, s[100:101]
	s_waitcnt vmcnt(16)
	v_lshlrev_b32_e32 v148, 16, v208
	v_and_b32_e32 v149, 0xffff0000, v208
	v_lshlrev_b32_e32 v150, 16, v209
	v_and_b32_e32 v151, 0xffff0000, v209
	v_lshlrev_b32_e32 v152, 16, v210
	v_and_b32_e32 v153, 0xffff0000, v210
	v_lshlrev_b32_e32 v154, 16, v211
	v_and_b32_e32 v155, 0xffff0000, v211
	v_pk_mul_f32 v[92:93], v[92:93], v[148:149]
	v_pk_mul_f32 v[94:95], v[94:95], v[150:151]
	v_pk_mul_f32 v[88:89], v[88:89], v[152:153]
	v_pk_mul_f32 v[90:91], v[90:91], v[154:155]
	v_lshlrev_b32_e32 v148, 16, v212
	v_and_b32_e32 v149, 0xffff0000, v212
	v_lshlrev_b32_e32 v150, 16, v213
	v_and_b32_e32 v151, 0xffff0000, v213
	v_lshlrev_b32_e32 v152, 16, v214
	v_and_b32_e32 v153, 0xffff0000, v214
	v_lshlrev_b32_e32 v154, 16, v215
	v_and_b32_e32 v155, 0xffff0000, v215
	v_pk_add_f32 v[92:93], v[92:93], v[148:149]
	v_pk_add_f32 v[94:95], v[94:95], v[150:151]
	v_pk_add_f32 v[88:89], v[88:89], v[152:153]
	v_pk_add_f32 v[90:91], v[90:91], v[154:155]
	v_cvt_pk_bf16_f32 v208, v92, v93
	v_cvt_pk_bf16_f32 v209, v94, v95
	v_cvt_pk_bf16_f32 v210, v88, v89
	v_cvt_pk_bf16_f32 v211, v90, v91
	global_store_dwordx4 v147, v[208:211], s[100:101]
	s_nop 1
	global_load_dwordx4 v[208:211], v136, s[72:73] offset:256
	global_load_dwordx4 v[212:215], v146, s[100:101] offset:256
	v_add_u32_e32 v136, 0x44000, v136
	v_add_u32_e32 v146, 0x10000, v146
	s_waitcnt vmcnt(17)
	v_lshlrev_b32_e32 v148, 16, v216
	v_and_b32_e32 v149, 0xffff0000, v216
	v_lshlrev_b32_e32 v150, 16, v217
	v_and_b32_e32 v151, 0xffff0000, v217
	v_lshlrev_b32_e32 v152, 16, v218
	v_and_b32_e32 v153, 0xffff0000, v218
	v_lshlrev_b32_e32 v154, 16, v219
	v_and_b32_e32 v155, 0xffff0000, v219
	v_pk_mul_f32 v[84:85], v[84:85], v[148:149]
	v_pk_mul_f32 v[86:87], v[86:87], v[150:151]
	v_pk_mul_f32 v[80:81], v[80:81], v[152:153]
	v_pk_mul_f32 v[82:83], v[82:83], v[154:155]
	v_lshlrev_b32_e32 v148, 16, v220
	v_and_b32_e32 v149, 0xffff0000, v220
	v_lshlrev_b32_e32 v150, 16, v221
	v_and_b32_e32 v151, 0xffff0000, v221
	v_lshlrev_b32_e32 v152, 16, v222
	v_and_b32_e32 v153, 0xffff0000, v222
	v_lshlrev_b32_e32 v154, 16, v223
	v_and_b32_e32 v155, 0xffff0000, v223
	v_pk_add_f32 v[84:85], v[84:85], v[148:149]
	v_pk_add_f32 v[86:87], v[86:87], v[150:151]
	v_pk_add_f32 v[80:81], v[80:81], v[152:153]
	v_pk_add_f32 v[82:83], v[82:83], v[154:155]
	v_cvt_pk_bf16_f32 v216, v84, v85
	v_cvt_pk_bf16_f32 v217, v86, v87
	v_cvt_pk_bf16_f32 v218, v80, v81
	v_cvt_pk_bf16_f32 v219, v82, v83
	global_store_dwordx4 v147, v[216:219], s[100:101] offset:256
	v_add_u32_e32 v147, 0x10000, v147
	s_nop 1
	global_load_dwordx4 v[216:219], v136, s[72:73]
	global_load_dwordx4 v[220:223], v146, s[100:101]
	s_waitcnt vmcnt(18)
; __device__ __forceinline__ unsigned cvt_pk_bf16(float lo, float hi) { unsigned r; asm volatile("v_cvt_pk_bf16_f32 %0, %1, %2" : "=v"(r) : "v"(lo), "v"(hi)); return r; }
; __device__ __forceinline__ float bflo(unsigned w) { return __uint_as_float(w << 16); }
; __device__ __forceinline__ float bfhi(unsigned w) { return __uint_as_float(w & 0xffff0000u); }
;     __device__ __forceinline__ void operator()(const f32x4 (&acc)[2][2][4][2], const Unit& u, int wr, int wc, int fr, int fq) const {
;     ...
;                     const u32x4 g = *(const u32x4*)(P + row * PLD + gcol + bj * HALF);
;                     bf16_t* mp = MG + row * 2048 + col0 + bj * HALF;
;                     float v[8];
;                     v[0] = acc[ai][bj][m][0][0] * bflo(g.x); v[1] = acc[ai][bj][m][0][1] * bfhi(g.x); v[2] = acc[ai][bj][m][0][2] * bflo(g.y); v[3] = acc[ai][bj][m][0][3] * bfhi(g.y);
;                     v[4] = acc[ai][bj][m][1][0] * bflo(g.z); v[5] = acc[ai][bj][m][1][1] * bfhi(g.z); v[6] = acc[ai][bj][m][1][2] * bflo(g.w); v[7] = acc[ai][bj][m][1][3] * bfhi(g.w);
;                     if (br) { const u32x4 p = *(const u32x4*)mp;
;                         v[0] += bflo(p.x); v[1] += bfhi(p.x); v[2] += bflo(p.y); v[3] += bfhi(p.y); v[4] += bflo(p.z); v[5] += bfhi(p.z); v[6] += bflo(p.w); v[7] += bfhi(p.w); }
;                     u32x4 w; w.x = cvt_pk_bf16(v[0], v[1]); w.y = cvt_pk_bf16(v[2], v[3]); w.z = cvt_pk_bf16(v[4], v[5]); w.w = cvt_pk_bf16(v[6], v[7]);
;                     *(u32x4*)mp = w; } }
	v_lshlrev_b32_e32 v148, 16, v180
	v_and_b32_e32 v149, 0xffff0000, v180
	v_lshlrev_b32_e32 v150, 16, v181
	v_and_b32_e32 v151, 0xffff0000, v181
	v_lshlrev_b32_e32 v152, 16, v182
	v_and_b32_e32 v153, 0xffff0000, v182
	v_lshlrev_b32_e32 v154, 16, v183
	v_and_b32_e32 v155, 0xffff0000, v183
	v_pk_mul_f32 v[76:77], v[76:77], v[148:149]
	v_pk_mul_f32 v[78:79], v[78:79], v[150:151]
	v_pk_mul_f32 v[72:73], v[72:73], v[152:153]
	v_pk_mul_f32 v[74:75], v[74:75], v[154:155]
	v_lshlrev_b32_e32 v148, 16, v188
	v_and_b32_e32 v149, 0xffff0000, v188
	v_lshlrev_b32_e32 v150, 16, v189
	v_and_b32_e32 v151, 0xffff0000, v189
	v_lshlrev_b32_e32 v152, 16, v190
	v_and_b32_e32 v153, 0xffff0000, v190
	v_lshlrev_b32_e32 v154, 16, v191
	v_and_b32_e32 v155, 0xffff0000, v191
	v_pk_add_f32 v[76:77], v[76:77], v[148:149]
	v_pk_add_f32 v[78:79], v[78:79], v[150:151]
	v_pk_add_f32 v[72:73], v[72:73], v[152:153]
	v_pk_add_f32 v[74:75], v[74:75], v[154:155]
	v_cvt_pk_bf16_f32 v180, v76, v77
	v_cvt_pk_bf16_f32 v181, v78, v79
	v_cvt_pk_bf16_f32 v182, v72, v73
	v_cvt_pk_bf16_f32 v183, v74, v75
	global_store_dwordx4 v147, v[180:183], s[100:101]
	s_nop 1
	global_load_dwordx4 v[180:183], v136, s[72:73] offset:256
	global_load_dwordx4 v[188:191], v146, s[100:101] offset:256
	v_add_u32_e32 v136, 0x44000, v136
	v_add_u32_e32 v146, 0x10000, v146
	s_waitcnt vmcnt(18)
	v_lshlrev_b32_e32 v148, 16, v164
	v_and_b32_e32 v149, 0xffff0000, v164
	v_lshlrev_b32_e32 v150, 16, v165
	v_and_b32_e32 v151, 0xffff0000, v165
	v_lshlrev_b32_e32 v152, 16, v166
	v_and_b32_e32 v153, 0xffff0000, v166
	v_lshlrev_b32_e32 v154, 16, v167
	v_and_b32_e32 v155, 0xffff0000, v167
	v_pk_mul_f32 v[68:69], v[68:69], v[148:149]
	v_pk_mul_f32 v[70:71], v[70:71], v[150:151]
	v_pk_mul_f32 v[64:65], v[64:65], v[152:153]
	v_pk_mul_f32 v[66:67], v[66:67], v[154:155]
	v_lshlrev_b32_e32 v148, 16, v168
	v_and_b32_e32 v149, 0xffff0000, v168
	v_lshlrev_b32_e32 v150, 16, v169
	v_and_b32_e32 v151, 0xffff0000, v169
	v_lshlrev_b32_e32 v152, 16, v170
	v_and_b32_e32 v153, 0xffff0000, v170
	v_lshlrev_b32_e32 v154, 16, v171
	v_and_b32_e32 v155, 0xffff0000, v171
	v_pk_add_f32 v[68:69], v[68:69], v[148:149]
	v_pk_add_f32 v[70:71], v[70:71], v[150:151]
	v_pk_add_f32 v[64:65], v[64:65], v[152:153]
	v_pk_add_f32 v[66:67], v[66:67], v[154:155]
	v_cvt_pk_bf16_f32 v164, v68, v69
	v_cvt_pk_bf16_f32 v165, v70, v71
	v_cvt_pk_bf16_f32 v166, v64, v65
	v_cvt_pk_bf16_f32 v167, v66, v67
	global_store_dwordx4 v147, v[164:167], s[100:101] offset:256
	v_add_u32_e32 v147, 0x50000, v147
	s_nop 1
	global_load_dwordx4 v[164:167], v136, s[72:73]
	global_load_dwordx4 v[168:171], v146, s[100:101]
	s_waitcnt vmcnt(18)
	v_lshlrev_b32_e32 v148, 16, v172
	v_and_b32_e32 v149, 0xffff0000, v172
	v_lshlrev_b32_e32 v150, 16, v173
	v_and_b32_e32 v151, 0xffff0000, v173
	v_lshlrev_b32_e32 v152, 16, v174
	v_and_b32_e32 v153, 0xffff0000, v174
	v_lshlrev_b32_e32 v154, 16, v175
	v_and_b32_e32 v155, 0xffff0000, v175
	v_pk_mul_f32 v[60:61], v[60:61], v[148:149]
	v_pk_mul_f32 v[62:63], v[62:63], v[150:151]
	v_pk_mul_f32 v[56:57], v[56:57], v[152:153]
	v_pk_mul_f32 v[58:59], v[58:59], v[154:155]
	v_lshlrev_b32_e32 v148, 16, v176
	v_and_b32_e32 v149, 0xffff0000, v176
	v_lshlrev_b32_e32 v150, 16, v177
	v_and_b32_e32 v151, 0xffff0000, v177
	v_lshlrev_b32_e32 v152, 16, v178
	v_and_b32_e32 v153, 0xffff0000, v178
	v_lshlrev_b32_e32 v154, 16, v179
	v_and_b32_e32 v155, 0xffff0000, v179
	v_pk_add_f32 v[60:61], v[60:61], v[148:149]
	v_pk_add_f32 v[62:63], v[62:63], v[150:151]
	v_pk_add_f32 v[56:57], v[56:57], v[152:153]
	v_pk_add_f32 v[58:59], v[58:59], v[154:155]
	v_cvt_pk_bf16_f32 v172, v60, v61
	v_cvt_pk_bf16_f32 v173, v62, v63
	v_cvt_pk_bf16_f32 v174, v56, v57
	v_cvt_pk_bf16_f32 v175, v58, v59
	global_store_dwordx4 v147, v[172:175], s[100:101]
	s_nop 1
	global_load_dwordx4 v[172:175], v136, s[72:73] offset:256
	global_load_dwordx4 v[176:179], v146, s[100:101] offset:256
	s_waitcnt vmcnt(18)
	v_lshlrev_b32_e32 v148, 16, v192
	v_and_b32_e32 v149, 0xffff0000, v192
	v_lshlrev_b32_e32 v150, 16, v193
	v_and_b32_e32 v151, 0xffff0000, v193
	v_lshlrev_b32_e32 v152, 16, v194
	v_and_b32_e32 v153, 0xffff0000, v194
	v_lshlrev_b32_e32 v154, 16, v195
	v_and_b32_e32 v155, 0xffff0000, v195
	v_pk_mul_f32 v[52:53], v[52:53], v[148:149]
	v_pk_mul_f32 v[54:55], v[54:55], v[150:151]
	v_pk_mul_f32 v[48:49], v[48:49], v[152:153]
	v_pk_mul_f32 v[50:51], v[50:51], v[154:155]
	v_lshlrev_b32_e32 v148, 16, v196
	v_and_b32_e32 v149, 0xffff0000, v196
	v_lshlrev_b32_e32 v150, 16, v197
	v_and_b32_e32 v151, 0xffff0000, v197
	v_lshlrev_b32_e32 v152, 16, v198
	v_and_b32_e32 v153, 0xffff0000, v198
	v_lshlrev_b32_e32 v154, 16, v199
	v_and_b32_e32 v155, 0xffff0000, v199
	v_pk_add_f32 v[52:53], v[52:53], v[148:149]
	v_pk_add_f32 v[54:55], v[54:55], v[150:151]
	v_pk_add_f32 v[48:49], v[48:49], v[152:153]
	v_pk_add_f32 v[50:51], v[50:51], v[154:155]
	v_cvt_pk_bf16_f32 v192, v52, v53
	v_cvt_pk_bf16_f32 v193, v54, v55
	v_cvt_pk_bf16_f32 v194, v48, v49
	v_cvt_pk_bf16_f32 v195, v50, v51
	global_store_dwordx4 v147, v[192:195], s[100:101] offset:256
	v_add_u32_e32 v147, 0x10000, v147
	s_waitcnt vmcnt(16)
; __device__ __forceinline__ unsigned cvt_pk_bf16(float lo, float hi) { unsigned r; asm volatile("v_cvt_pk_bf16_f32 %0, %1, %2" : "=v"(r) : "v"(lo), "v"(hi)); return r; }
; __device__ __forceinline__ float bflo(unsigned w) { return __uint_as_float(w << 16); }
; __device__ __forceinline__ float bfhi(unsigned w) { return __uint_as_float(w & 0xffff0000u); }
;     __device__ __forceinline__ void operator()(const f32x4 (&acc)[2][2][4][2], const Unit& u, int wr, int wc, int fr, int fq) const {
;     ...
;                     const u32x4 g = *(const u32x4*)(P + row * PLD + gcol + bj * HALF);
;                     bf16_t* mp = MG + row * 2048 + col0 + bj * HALF;
;                     float v[8];
;                     v[0] = acc[ai][bj][m][0][0] * bflo(g.x); v[1] = acc[ai][bj][m][0][1] * bfhi(g.x); v[2] = acc[ai][bj][m][0][2] * bflo(g.y); v[3] = acc[ai][bj][m][0][3] * bfhi(g.y);
;                     v[4] = acc[ai][bj][m][1][0] * bflo(g.z); v[5] = acc[ai][bj][m][1][1] * bfhi(g.z); v[6] = acc[ai][bj][m][1][2] * bflo(g.w); v[7] = acc[ai][bj][m][1][3] * bfhi(g.w);
;                     if (br) { const u32x4 p = *(const u32x4*)mp;
;                         v[0] += bflo(p.x); v[1] += bfhi(p.x); v[2] += bflo(p.y); v[3] += bfhi(p.y); v[4] += bflo(p.z); v[5] += bfhi(p.z); v[6] += bflo(p.w); v[7] += bfhi(p.w); }
;                     u32x4 w; w.x = cvt_pk_bf16(v[0], v[1]); w.y = cvt_pk_bf16(v[2], v[3]); w.z = cvt_pk_bf16(v[4], v[5]); w.w = cvt_pk_bf16(v[6], v[7]);
;                     *(u32x4*)mp = w; } }
	v_lshlrev_b32_e32 v148, 16, v200
	v_and_b32_e32 v149, 0xffff0000, v200
	v_lshlrev_b32_e32 v150, 16, v201
	v_and_b32_e32 v151, 0xffff0000, v201
	v_lshlrev_b32_e32 v152, 16, v202
	v_and_b32_e32 v153, 0xffff0000, v202
	v_lshlrev_b32_e32 v154, 16, v203
	v_and_b32_e32 v155, 0xffff0000, v203
	v_pk_mul_f32 v[44:45], v[44:45], v[148:149]
	v_pk_mul_f32 v[46:47], v[46:47], v[150:151]
	v_pk_mul_f32 v[40:41], v[40:41], v[152:153]
	v_pk_mul_f32 v[42:43], v[42:43], v[154:155]
	v_lshlrev_b32_e32 v148, 16, v204
	v_and_b32_e32 v149, 0xffff0000, v204
	v_lshlrev_b32_e32 v150, 16, v205
	v_and_b32_e32 v151, 0xffff0000, v205
	v_lshlrev_b32_e32 v152, 16, v206
	v_and_b32_e32 v153, 0xffff0000, v206
	v_lshlrev_b32_e32 v154, 16, v207
	v_and_b32_e32 v155, 0xffff0000, v207
	v_pk_add_f32 v[44:45], v[44:45], v[148:149]
	v_pk_add_f32 v[46:47], v[46:47], v[150:151]
	v_pk_add_f32 v[40:41], v[40:41], v[152:153]
	v_pk_add_f32 v[42:43], v[42:43], v[154:155]
	v_cvt_pk_bf16_f32 v200, v44, v45
	v_cvt_pk_bf16_f32 v201, v46, v47
	v_cvt_pk_bf16_f32 v202, v40, v41
	v_cvt_pk_bf16_f32 v203, v42, v43
	global_store_dwordx4 v147, v[200:203], s[100:101]
	s_waitcnt vmcnt(14)
	v_lshlrev_b32_e32 v148, 16, v208
	v_and_b32_e32 v149, 0xffff0000, v208
	v_lshlrev_b32_e32 v150, 16, v209
	v_and_b32_e32 v151, 0xffff0000, v209
	v_lshlrev_b32_e32 v152, 16, v210
	v_and_b32_e32 v153, 0xffff0000, v210
	v_lshlrev_b32_e32 v154, 16, v211
	v_and_b32_e32 v155, 0xffff0000, v211
	v_pk_mul_f32 v[36:37], v[36:37], v[148:149]
	v_pk_mul_f32 v[38:39], v[38:39], v[150:151]
	v_pk_mul_f32 v[32:33], v[32:33], v[152:153]
	v_pk_mul_f32 v[34:35], v[34:35], v[154:155]
	v_lshlrev_b32_e32 v148, 16, v212
	v_and_b32_e32 v149, 0xffff0000, v212
	v_lshlrev_b32_e32 v150, 16, v213
	v_and_b32_e32 v151, 0xffff0000, v213
	v_lshlrev_b32_e32 v152, 16, v214
	v_and_b32_e32 v153, 0xffff0000, v214
	v_lshlrev_b32_e32 v154, 16, v215
	v_and_b32_e32 v155, 0xffff0000, v215
	v_pk_add_f32 v[36:37], v[36:37], v[148:149]
	v_pk_add_f32 v[38:39], v[38:39], v[150:151]
	v_pk_add_f32 v[32:33], v[32:33], v[152:153]
	v_pk_add_f32 v[34:35], v[34:35], v[154:155]
	v_cvt_pk_bf16_f32 v208, v36, v37
	v_cvt_pk_bf16_f32 v209, v38, v39
	v_cvt_pk_bf16_f32 v210, v32, v33
	v_cvt_pk_bf16_f32 v211, v34, v35
	global_store_dwordx4 v147, v[208:211], s[100:101] offset:256
	v_add_u32_e32 v147, 0x10000, v147
	s_waitcnt vmcnt(12)
	v_lshlrev_b32_e32 v148, 16, v216
	v_and_b32_e32 v149, 0xffff0000, v216
	v_lshlrev_b32_e32 v150, 16, v217
	v_and_b32_e32 v151, 0xffff0000, v217
	v_lshlrev_b32_e32 v152, 16, v218
	v_and_b32_e32 v153, 0xffff0000, v218
	v_lshlrev_b32_e32 v154, 16, v219
	v_and_b32_e32 v155, 0xffff0000, v219
	v_pk_mul_f32 v[28:29], v[28:29], v[148:149]
	v_pk_mul_f32 v[30:31], v[30:31], v[150:151]
	v_pk_mul_f32 v[24:25], v[24:25], v[152:153]
	v_pk_mul_f32 v[26:27], v[26:27], v[154:155]
	v_lshlrev_b32_e32 v148, 16, v220
	v_and_b32_e32 v149, 0xffff0000, v220
	v_lshlrev_b32_e32 v150, 16, v221
	v_and_b32_e32 v151, 0xffff0000, v221
	v_lshlrev_b32_e32 v152, 16, v222
	v_and_b32_e32 v153, 0xffff0000, v222
	v_lshlrev_b32_e32 v154, 16, v223
	v_and_b32_e32 v155, 0xffff0000, v223
	v_pk_add_f32 v[28:29], v[28:29], v[148:149]
	v_pk_add_f32 v[30:31], v[30:31], v[150:151]
	v_pk_add_f32 v[24:25], v[24:25], v[152:153]
	v_pk_add_f32 v[26:27], v[26:27], v[154:155]
	v_cvt_pk_bf16_f32 v216, v28, v29
	v_cvt_pk_bf16_f32 v217, v30, v31
	v_cvt_pk_bf16_f32 v218, v24, v25
	v_cvt_pk_bf16_f32 v219, v26, v27
	global_store_dwordx4 v147, v[216:219], s[100:101]
	s_waitcnt vmcnt(10)
	v_lshlrev_b32_e32 v148, 16, v180
	v_and_b32_e32 v149, 0xffff0000, v180
	v_lshlrev_b32_e32 v150, 16, v181
	v_and_b32_e32 v151, 0xffff0000, v181
	v_lshlrev_b32_e32 v152, 16, v182
	v_and_b32_e32 v153, 0xffff0000, v182
	v_lshlrev_b32_e32 v154, 16, v183
	v_and_b32_e32 v155, 0xffff0000, v183
	v_pk_mul_f32 v[20:21], v[20:21], v[148:149]
	v_pk_mul_f32 v[22:23], v[22:23], v[150:151]
	v_pk_mul_f32 v[16:17], v[16:17], v[152:153]
	v_pk_mul_f32 v[18:19], v[18:19], v[154:155]
	v_lshlrev_b32_e32 v148, 16, v188
	v_and_b32_e32 v149, 0xffff0000, v188
	v_lshlrev_b32_e32 v150, 16, v189
	v_and_b32_e32 v151, 0xffff0000, v189
	v_lshlrev_b32_e32 v152, 16, v190
	v_and_b32_e32 v153, 0xffff0000, v190
	v_lshlrev_b32_e32 v154, 16, v191
	v_and_b32_e32 v155, 0xffff0000, v191
	v_pk_add_f32 v[20:21], v[20:21], v[148:149]
	v_pk_add_f32 v[22:23], v[22:23], v[150:151]
	v_pk_add_f32 v[16:17], v[16:17], v[152:153]
	v_pk_add_f32 v[18:19], v[18:19], v[154:155]
	v_cvt_pk_bf16_f32 v180, v20, v21
	v_cvt_pk_bf16_f32 v181, v22, v23
	v_cvt_pk_bf16_f32 v182, v16, v17
	v_cvt_pk_bf16_f32 v183, v18, v19
	global_store_dwordx4 v147, v[180:183], s[100:101] offset:256
	v_add_u32_e32 v147, 0x10000, v147
	s_waitcnt vmcnt(8)
	v_lshlrev_b32_e32 v148, 16, v164
	v_and_b32_e32 v149, 0xffff0000, v164
	v_lshlrev_b32_e32 v150, 16, v165
	v_and_b32_e32 v151, 0xffff0000, v165
	v_lshlrev_b32_e32 v152, 16, v166
	v_and_b32_e32 v153, 0xffff0000, v166
	v_lshlrev_b32_e32 v154, 16, v167
	v_and_b32_e32 v155, 0xffff0000, v167
	v_pk_mul_f32 v[12:13], v[12:13], v[148:149]
	v_pk_mul_f32 v[14:15], v[14:15], v[150:151]
	v_pk_mul_f32 v[8:9], v[8:9], v[152:153]
	v_pk_mul_f32 v[10:11], v[10:11], v[154:155]
	v_lshlrev_b32_e32 v148, 16, v168
	v_and_b32_e32 v149, 0xffff0000, v168
	v_lshlrev_b32_e32 v150, 16, v169
	v_and_b32_e32 v151, 0xffff0000, v169
	v_lshlrev_b32_e32 v152, 16, v170
	v_and_b32_e32 v153, 0xffff0000, v170
	v_lshlrev_b32_e32 v154, 16, v171
	v_and_b32_e32 v155, 0xffff0000, v171
	v_pk_add_f32 v[12:13], v[12:13], v[148:149]
	v_pk_add_f32 v[14:15], v[14:15], v[150:151]
	v_pk_add_f32 v[8:9], v[8:9], v[152:153]
	v_pk_add_f32 v[10:11], v[10:11], v[154:155]
	v_cvt_pk_bf16_f32 v164, v12, v13
	v_cvt_pk_bf16_f32 v165, v14, v15
	v_cvt_pk_bf16_f32 v166, v8, v9
	v_cvt_pk_bf16_f32 v167, v10, v11
	global_store_dwordx4 v147, v[164:167], s[100:101]
	s_waitcnt vmcnt(6)
	v_lshlrev_b32_e32 v148, 16, v172
	v_and_b32_e32 v149, 0xffff0000, v172
	v_lshlrev_b32_e32 v150, 16, v173
	v_and_b32_e32 v151, 0xffff0000, v173
	v_lshlrev_b32_e32 v152, 16, v174
	v_and_b32_e32 v153, 0xffff0000, v174
	v_lshlrev_b32_e32 v154, 16, v175
	v_and_b32_e32 v155, 0xffff0000, v175
	v_pk_mul_f32 v[4:5], v[4:5], v[148:149]
	v_pk_mul_f32 v[6:7], v[6:7], v[150:151]
	v_pk_mul_f32 v[0:1], v[0:1], v[152:153]
	v_pk_mul_f32 v[2:3], v[2:3], v[154:155]
	v_lshlrev_b32_e32 v148, 16, v176
	v_and_b32_e32 v149, 0xffff0000, v176
	v_lshlrev_b32_e32 v150, 16, v177
	v_and_b32_e32 v151, 0xffff0000, v177
	v_lshlrev_b32_e32 v152, 16, v178
	v_and_b32_e32 v153, 0xffff0000, v178
	v_lshlrev_b32_e32 v154, 16, v179
	v_and_b32_e32 v155, 0xffff0000, v179
	v_pk_add_f32 v[4:5], v[4:5], v[148:149]
	v_pk_add_f32 v[6:7], v[6:7], v[150:151]
	v_pk_add_f32 v[0:1], v[0:1], v[152:153]
	v_pk_add_f32 v[2:3], v[2:3], v[154:155]
	v_cvt_pk_bf16_f32 v172, v4, v5
	v_cvt_pk_bf16_f32 v173, v6, v7
	v_cvt_pk_bf16_f32 v174, v0, v1
	v_cvt_pk_bf16_f32 v175, v2, v3
	global_store_dwordx4 v147, v[172:175], s[100:101] offset:256
;     __device__ __forceinline__ void operator()(const f32x4 (&acc)[2][2][4][2], const Unit& u, int wr, int wc, int fr, int fq) const {
;     ...
;                     *(u32x4*)mp = w; } }
.Lp4epi_done:
	s_andn2_b64 vcc, exec, s[4:5]
	s_mov_b64 s[4:5], -1
	s_cbranch_vccnz .LBB0_564
	s_andn2_b64 vcc, exec, s[2:3]
	s_cbranch_vccnz .LBB0_563
	s_barrier
	s_branch .LBB0_563
